# attention phases (P5, P14): one static s_setprio 1 for the younger wave half (waves 4-7), reset at phase end
# baseline (speedup 1.0000x reference)
; #define LAS __attribute__((address_space(3)))
; __device__ __forceinline__ unsigned xb_xcc_id() { return (unsigned)__builtin_amdgcn_s_getreg((3 << 11) | 20) & 0xFu; }
; #define PH(k) if (((PHMASK >> (k)) & 1) && lo <= (k) && (k) < hi) for (int rep_ = 0; rep_ < 1 + ((REPMASK >> (k)) & 1); ++rep_)
; __global__ void __launch_bounds__(512, 2) fwd_kernel(Params p) {
;     ...
;     PH(5) { PHASE_BEGIN; if (rep_) grid.sync();
;         const int x0 = (int)(xb_xcc_id() & 7u);
;         for (int qi = 0; qi < 8; ++qi) { const int q = (x0 + qi) & 7;
;             for (;;) {
;                 if (tid == 0) *s_item = (int)atomicAdd(ctl + 8 * q, 1u);
;                 __syncthreads(); const int li = *s_item; __syncthreads();
;                 if (li >= 128) break;
;                 if (li < 96) { const int qb = 31 - li / 3, bh = q + 8 * (li % 3), b = bh / NHEAD, h = bh % NHEAD; const size_t r0 = (size_t)b * SEQ;
;                     att::attn_block<192, true>(Qb + (r0 + qb * 256) * QW + h * QKD, QW, Kb + r0 * QW + h * QKD, QW, kvb + r0 * KVW + h * 256 + 128, KVW,
;                                                mixed0 + (r0 + qb * 256) * DM + h * 128, DM, qb * 256, 4 * (qb + 1), 0.07216878364870322f, (LAS char*)lds);
.LBB0_667:
	s_cmp_lt_i32 s80, 6
	s_cselect_b64 s[2:3], -1, 0
	s_and_b64 s[0:1], s[2:3], s[4:5]
	s_andn2_b64 vcc, exec, s[0:1]
	s_cbranch_vccnz .LBB0_705
	v_readfirstlane_b32 s101, v193
	s_nop 3
	s_lshr_b32 s101, s101, 6
	s_cmp_ge_u32 s101, 4
	s_cbranch_scc0 .Lattn_prio_done_1
	s_setprio 1
.Lattn_prio_done_1:
	v_mov_b32_e32 v0, v193
	v_writelane_b32 v250, s84, 0
	v_writelane_b32 v250, s2, 1
	v_mov_b32_e32 v1, 0
	s_movk_i32 s1, 0x900
	v_writelane_b32 v250, s3, 2
	v_writelane_b32 v250, s82, 3
	s_mov_b64 s[86:87], 0x48000
	v_mov_b32_e32 v137, 0xffffff80
	v_writelane_b32 v250, s83, 4
	s_waitcnt lgkmcnt(0)
	v_writelane_b32 v250, s75, 5
	v_writelane_b32 v250, s80, 6
	s_mov_b32 s83, 0
	v_mov_b32_e32 v138, 0x80
	v_writelane_b32 v250, s81, 7
	v_writelane_b32 v250, s78, 8
	s_mov_b32 s80, 0xc000
	s_movk_i32 s81, 0x60
	v_writelane_b32 v250, s79, 9
	s_load_dwordx4 s[72:75], s[78:79], 0xd8
	s_getreg_b32 s2, hwreg(HW_REG_XCC_ID, 0, 4)
	v_cmp_eq_u32_e64 s[4:5], 0, v0
	v_mov_b32_e32 v139, 0xff800000
	s_mov_b32 s77, 0
	s_waitcnt lgkmcnt(0)
	s_add_u32 s94, s74, 0x8000000
	s_addc_u32 s95, s75, 0
	s_add_u32 s0, s74, 0x3660000
	v_writelane_b32 v250, s0, 10
	s_addc_u32 s0, s75, 0
	v_writelane_b32 v250, s0, 11
	s_add_u32 s0, s74, 0x36e0000
	v_writelane_b32 v250, s0, 12
	s_addc_u32 s0, s75, 0
	v_writelane_b32 v250, s0, 13
	s_add_u32 s0, s74, 0x1a000000
	v_writelane_b32 v250, s0, 14
	s_addc_u32 s0, s75, 0
	s_add_i32 s79, 0, 0x21000
	v_writelane_b32 v250, s0, 15
	v_mov_b32_e32 v136, s79
	s_mov_b32 s0, 0x41000000
	v_writelane_b32 v250, s2, 16
	s_branch .LBB0_670

; __device__ __forceinline__ unsigned xb_ld(unsigned* p)              { return __hip_atomic_load(p, __ATOMIC_RELAXED, __HIP_MEMORY_SCOPE_AGENT); }
; __device__ __forceinline__ void xcd_barrier_complete(unsigned* bar, unsigned x, unsigned& nloc, unsigned& nx) {
;     const unsigned G = gridDim.x * gridDim.y * gridDim.z;
;     unsigned sum, cnt, mine, sp = 0u;
;     for (;;) {
;         sum = 0u; cnt = 0u; mine = 0u;
; #pragma unroll
;         for (unsigned j = 0; j < 16; ++j) { const unsigned c = xb_ld(&bar[XB_XCNT(j)]); sum += c; cnt += (c > 0u) ? 1u : 0u; mine = (j == x) ? c : mine; }
; __device__ __forceinline__ void xcd_barrier(const XcdBarrier& b) {
;     asm volatile("s_waitcnt vmcnt(0)" ::: "memory");
;     __syncthreads();
;     if (threadIdx.x == 0) {
;         unsigned* bar = b.bar;
;         __builtin_amdgcn_s_waitcnt(0);
;         unsigned nloc = b.st[0], nx = b.st[1];
;         if (nloc == 0u) { xcd_barrier_complete(bar, b.x, nloc, nx); b.st[0] = nloc; b.st[1] = nx; }
.LBB0_705:
	s_setprio 0
	s_cmp_gt_i32 s81, 6
	s_cselect_b64 s[4:5], -1, 0
	s_and_b64 s[0:1], s[2:3], s[4:5]
	s_andn2_b64 vcc, exec, s[0:1]
	s_cbranch_vccnz .LBB0_759
	s_mov_b64 s[8:9], s[78:79]
	s_getreg_b32 s0, hwreg(HW_REG_XCC_ID, 0, 4)
	s_waitcnt vmcnt(0)
	s_waitcnt vmcnt(0) lgkmcnt(0)
	s_barrier
	s_and_saveexec_b64 s[6:7], s[82:83]
	s_cbranch_execz .LBB0_758
	s_add_i32 s1, 0, 0x21020
	v_mov_b32_e32 v0, s1
	s_load_dwordx2 s[8:9], s[8:9], 0xe0
	s_waitcnt vmcnt(0) expcnt(0) lgkmcnt(0)
	ds_read_b32 v2, v0
	s_add_i32 s1, 0, 0x21024
	v_mov_b32_e32 v0, s1
	ds_read_b32 v0, v0
	s_and_b32 s0, s0, 15
	s_waitcnt lgkmcnt(1)
	v_cmp_ne_u32_e32 vcc, 0, v2
	s_cbranch_vccnz .LBB0_722
	s_add_u32 s10, s8, 0x4200
	s_addc_u32 s11, s9, 0
	s_add_u32 s12, s8, 0x4400
	s_addc_u32 s13, s9, 0
	s_add_u32 s14, s8, 0x4500
	s_addc_u32 s15, s9, 0
	s_add_u32 s16, s8, 0x4600
	s_addc_u32 s17, s9, 0
	s_add_u32 s18, s8, 0x4700
	s_addc_u32 s19, s9, 0
	s_add_u32 s20, s8, 0x4800
	s_addc_u32 s21, s9, 0
	s_add_u32 s22, s8, 0x4900
	s_addc_u32 s23, s9, 0
	s_add_u32 s24, s8, 0x4a00
	s_addc_u32 s25, s9, 0
	s_add_u32 s26, s8, 0x4b00
	s_addc_u32 s27, s9, 0
	s_add_u32 s28, s8, 0x4c00
	s_addc_u32 s29, s9, 0
	s_add_u32 s30, s8, 0x4d00
	s_addc_u32 s31, s9, 0
	s_add_u32 s34, s8, 0x4e00
	s_addc_u32 s35, s9, 0
	s_add_u32 s36, s8, 0x4f00
	s_addc_u32 s37, s9, 0
	s_add_u32 s40, s8, 0x5000
	s_addc_u32 s41, s9, 0
	s_add_u32 s42, s8, 0x5100
	s_addc_u32 s43, s9, 0
	s_add_u32 s44, s8, 0x5200
	s_addc_u32 s45, s9, 0
	s_mul_i32 s1, s77, s75
	s_add_u32 s46, s8, 0x5300
	s_mul_i32 s1, s1, s76
	s_addc_u32 s47, s9, 0
	s_mov_b32 s2, 1
	v_mov_b32_e32 v16, 0
	s_branch .LBB0_710

; #define PH(k) if (((PHMASK >> (k)) & 1) && lo <= (k) && (k) < hi) for (int rep_ = 0; rep_ < 1 + ((REPMASK >> (k)) & 1); ++rep_)
; __global__ void __launch_bounds__(512, 2) fwd_kernel(Params p) {
;     ...
;     PH(14) { PHASE_BEGIN;
;         for (int it = bx; it < NB * NCHUNK; it += G) { const int ch = it % NCHUNK, b = it / NCHUNK;
;             if (tid < LRU_W / 4) { const int c = tid * 4; const size_t base = ((size_t)b * SEQ + (size_t)ch * CHL) * LRU_W + c; float h[4] = {0.f, 0.f, 0.f, 0.f}, Pp[4] = {1.f, 1.f, 1.f, 1.f};
; #pragma unroll 8
;                 for (int s = 0; s < CHL; ++s) { const u32x2 aw = *(const u32x2*)(ascan + base + (size_t)s * LRU_W), bw = *(const u32x2*)(bscan + base + (size_t)s * LRU_W), xw = *(const u32x2*)(xcb + base + (size_t)s * LRU_W);
.LBB0_1422:
	s_cmp_lt_i32 s80, 15
	s_cselect_b64 s[8:9], -1, 0
	s_and_b64 s[0:1], s[8:9], s[4:5]
	s_andn2_b64 vcc, exec, s[0:1]
	s_cbranch_vccnz .LBB0_1442
	v_readfirstlane_b32 s101, v193
	s_nop 3
	s_lshr_b32 s101, s101, 6
	s_cmp_ge_u32 s101, 4
	s_cbranch_scc0 .Lattn_prio_done_2
	s_setprio 1
.Lattn_prio_done_2:
	s_cmpk_gt_i32 s84, 0xff
	s_mov_b64 s[4:5], s[78:79]
	v_mov_b32_e32 v0, v193
	s_cbranch_scc1 .LBB0_1442
	s_load_dwordx2 s[10:11], s[4:5], 0xe0
	s_waitcnt vmcnt(0)
	v_lshlrev_b32_e32 v8, 2, v0
	s_movk_i32 s0, 0x180
	v_ashrrev_i32_e32 v9, 31, v8
	v_cmp_gt_i32_e64 s[4:5], s0, v0
	s_waitcnt lgkmcnt(0)
	v_lshl_add_u64 v[0:1], v[8:9], 2, s[10:11]
	s_mov_b64 s[0:1], 0x3b60000
	v_lshl_add_u64 v[10:11], v[0:1], 0, s[0:1]
	s_mov_b64 s[0:1], 0x3ce0000
	v_lshl_add_u64 v[12:13], v[0:1], 0, s[0:1]
	v_lshl_add_u64 v[14:15], v[8:9], 1, s[10:11]
	s_mov_b32 s0, 0x1a001000
	s_mov_b32 s1, 0x13001000
	s_mov_b32 s2, 0x17001000
	s_mov_b32 s3, 0x1a002000
	s_mov_b32 s18, 0x13002000
	s_mov_b32 s19, 0x17002000
	s_mov_b32 s20, 0x1a003000
	s_mov_b32 s21, 0x13003000
	s_mov_b32 s22, 0x17003000
	s_mov_b32 s23, 0x1a004000
	s_mov_b32 s24, 0x13004000
	s_mov_b32 s25, 0x17004000
	s_mov_b32 s26, 0x1a005000
	s_mov_b32 s27, 0x13005000
	s_mov_b32 s28, 0x17005000
	v_mov_b32_e32 v22, 0x1800
	s_mov_b32 s29, s84
	s_branch .LBB0_1426

; __device__ __forceinline__ unsigned xb_ld(unsigned* p)              { return __hip_atomic_load(p, __ATOMIC_RELAXED, __HIP_MEMORY_SCOPE_AGENT); }
; __device__ __forceinline__ void xcd_barrier_complete(unsigned* bar, unsigned x, unsigned& nloc, unsigned& nx) {
;     const unsigned G = gridDim.x * gridDim.y * gridDim.z;
;     unsigned sum, cnt, mine, sp = 0u;
;     for (;;) {
;         sum = 0u; cnt = 0u; mine = 0u;
; #pragma unroll
;         for (unsigned j = 0; j < 16; ++j) { const unsigned c = xb_ld(&bar[XB_XCNT(j)]); sum += c; cnt += (c > 0u) ? 1u : 0u; mine = (j == x) ? c : mine; }
; __device__ __forceinline__ void xcd_barrier(const XcdBarrier& b) {
;     asm volatile("s_waitcnt vmcnt(0)" ::: "memory");
;     __syncthreads();
;     if (threadIdx.x == 0) {
;         unsigned* bar = b.bar;
;         __builtin_amdgcn_s_waitcnt(0);
;         unsigned nloc = b.st[0], nx = b.st[1];
;         if (nloc == 0u) { xcd_barrier_complete(bar, b.x, nloc, nx); b.st[0] = nloc; b.st[1] = nx; }
.LBB0_1442:
	s_setprio 0
	s_cmp_gt_i32 s81, 15
	s_cselect_b64 s[4:5], -1, 0
	s_and_b64 s[0:1], s[8:9], s[4:5]
	s_andn2_b64 vcc, exec, s[0:1]
	s_cbranch_vccnz .LBB0_1496
	s_mov_b64 s[8:9], s[78:79]
	s_getreg_b32 s0, hwreg(HW_REG_XCC_ID, 0, 4)
	s_waitcnt vmcnt(0)
	s_waitcnt vmcnt(0) lgkmcnt(0)
	s_barrier
	s_and_saveexec_b64 s[6:7], s[82:83]
	s_cbranch_execz .LBB0_1495
	s_add_i32 s1, 0, 0x21020
	v_mov_b32_e32 v0, s1
	s_load_dwordx2 s[8:9], s[8:9], 0xe0
	s_waitcnt vmcnt(0) expcnt(0) lgkmcnt(0)
	ds_read_b32 v2, v0
	s_add_i32 s1, 0, 0x21024
	v_mov_b32_e32 v0, s1
	ds_read_b32 v0, v0
	s_and_b32 s0, s0, 15
	s_waitcnt lgkmcnt(1)
	v_cmp_ne_u32_e32 vcc, 0, v2
	s_cbranch_vccnz .LBB0_1459
	s_add_u32 s10, s8, 0x4200
	s_addc_u32 s11, s9, 0
	s_add_u32 s12, s8, 0x4400
	s_addc_u32 s13, s9, 0
	s_add_u32 s14, s8, 0x4500
	s_addc_u32 s15, s9, 0
	s_add_u32 s16, s8, 0x4600
	s_addc_u32 s17, s9, 0
	s_add_u32 s18, s8, 0x4700
	s_addc_u32 s19, s9, 0
	s_add_u32 s20, s8, 0x4800
	s_addc_u32 s21, s9, 0
	s_add_u32 s22, s8, 0x4900
	s_addc_u32 s23, s9, 0
	s_add_u32 s24, s8, 0x4a00
	s_addc_u32 s25, s9, 0
	s_add_u32 s26, s8, 0x4b00
	s_addc_u32 s27, s9, 0
	s_add_u32 s28, s8, 0x4c00
	s_addc_u32 s29, s9, 0
	s_add_u32 s30, s8, 0x4d00
	s_addc_u32 s31, s9, 0
	s_add_u32 s34, s8, 0x4e00
	s_addc_u32 s35, s9, 0
	s_add_u32 s36, s8, 0x4f00
	s_addc_u32 s37, s9, 0
	s_add_u32 s40, s8, 0x5000
	s_addc_u32 s41, s9, 0
	s_add_u32 s42, s8, 0x5100
	s_addc_u32 s43, s9, 0
	s_add_u32 s44, s8, 0x5200
	s_addc_u32 s45, s9, 0
	s_mul_i32 s1, s77, s75
	s_add_u32 s46, s8, 0x5300
	s_mul_i32 s1, s1, s76
	s_addc_u32 s47, s9, 0
	s_mov_b32 s2, 1
	v_mov_b32_e32 v16, 0
	s_branch .LBB0_1447
